# nt hint on the 16 bf16 output stores of the w_in GEMM epilogue (streaming output, keeps A/B tiles in L2)
# speedup vs baseline: 1.0139x; 1.0057x over previous
; __device__ __forceinline__ unsigned pk2(float lo, float hi) { f32x2 v = {lo, hi}; bf16x2_t b = __builtin_convertvector(v, bf16x2_t); return __builtin_bit_cast(unsigned, b); }
; __device__ __forceinline__ float sigmoidf_(float x) { return rcpf_(1.f + ex2(-x * LOG2E)); }
;     __device__ __forceinline__ void operator()(const f32x4 (&acc)[2][2][4][2], const Unit& u, int wr, int wc, int fr, int fq) const {
;     ...
; #pragma unroll
;         for (int ai = 0; ai < 2; ++ai)
; #pragma unroll
;             for (int m = 0; m < 4; ++m) {
;                 bf16_t* rowp = gate ? G + ((size_t)((((u.pn - gate0 / BM) >> 3) * 64 + u.pm) * 8 + ((u.pn - gate0 / BM) & 7)) * 256 + (wr * 64 + fr + ai * HALF + m * 16)) * 256 + wc * 32 + 8 * fq
;                                     : O + (size_t)(row0 + ai * HALF + m * 16) * ldc + col0;
; #pragma unroll
;                 for (int bj = 0; bj < 2; ++bj) { f32x4 v0 = acc[ai][bj][m][0], v1 = acc[ai][bj][m][1];
;                     if (gate) {
; #pragma unroll
;                         for (int j = 0; j < 4; ++j) { v0[j] = sigmoidf_(v0[j] + gb[bj][0][j]); v1[j] = sigmoidf_(v1[j] + gb[bj][1][j]); } }
;                     u32x4 w; w.x = pk2(v0[0], v0[1]); w.y = pk2(v0[2], v0[3]); w.z = pk2(v1[0], v1[1]); w.w = pk2(v1[2], v1[3]);
;                     *(u32x4*)(rowp + bj * HALF) = w; } }
.LBB0_148:
	v_cvt_pk_bf16_f32 v142, v142, v143
	v_cvt_pk_bf16_f32 v143, v144, v145
	v_cvt_pk_bf16_f32 v144, v138, v139
	v_cvt_pk_bf16_f32 v145, v140, v141
	s_and_b64 vcc, exec, s[6:7]
	s_mov_b64 s[24:25], -1
	global_store_dwordx4 v[178:179], v[142:145], off nt
	s_cbranch_vccnz .LBB0_150
	s_mov_b64 s[24:25], 0

; __device__ __forceinline__ unsigned pk2(float lo, float hi) { f32x2 v = {lo, hi}; bf16x2_t b = __builtin_convertvector(v, bf16x2_t); return __builtin_bit_cast(unsigned, b); }
; __device__ __forceinline__ float sigmoidf_(float x) { return rcpf_(1.f + ex2(-x * LOG2E)); }
;     __device__ __forceinline__ void operator()(const f32x4 (&acc)[2][2][4][2], const Unit& u, int wr, int wc, int fr, int fq) const {
;     ...
; #pragma unroll
;         for (int ai = 0; ai < 2; ++ai)
; #pragma unroll
;             for (int m = 0; m < 4; ++m) {
;                 bf16_t* rowp = gate ? G + ((size_t)((((u.pn - gate0 / BM) >> 3) * 64 + u.pm) * 8 + ((u.pn - gate0 / BM) & 7)) * 256 + (wr * 64 + fr + ai * HALF + m * 16)) * 256 + wc * 32 + 8 * fq
;                                     : O + (size_t)(row0 + ai * HALF + m * 16) * ldc + col0;
; #pragma unroll
;                 for (int bj = 0; bj < 2; ++bj) { f32x4 v0 = acc[ai][bj][m][0], v1 = acc[ai][bj][m][1];
;                     if (gate) {
; #pragma unroll
;                         for (int j = 0; j < 4; ++j) { v0[j] = sigmoidf_(v0[j] + gb[bj][0][j]); v1[j] = sigmoidf_(v1[j] + gb[bj][1][j]); } }
;                     u32x4 w; w.x = pk2(v0[0], v0[1]); w.y = pk2(v0[2], v0[3]); w.z = pk2(v1[0], v1[1]); w.w = pk2(v1[2], v1[3]);
;                     *(u32x4*)(rowp + bj * HALF) = w; } }
.LBB0_152:
	v_cvt_pk_bf16_f32 v134, v134, v135
	v_cvt_pk_bf16_f32 v135, v136, v137
	v_cvt_pk_bf16_f32 v136, v130, v131
	v_cvt_pk_bf16_f32 v137, v132, v133
	s_and_b64 vcc, exec, s[6:7]
	s_mov_b64 s[24:25], -1
	global_store_dwordx4 v[178:179], v[134:137], off offset:256 nt
	s_cbranch_vccnz .LBB0_156
	v_or_b32_e32 v130, 16, v176
	v_ashrrev_i32_e32 v131, 31, v130
	v_lshlrev_b64 v[130:131], 14, v[130:131]
	v_lshl_add_u64 v[130:131], s[2:3], 0, v[130:131]
	v_lshl_add_u64 v[130:131], v[174:175], 1, v[130:131]
	s_cbranch_execz .LBB0_157

; __device__ __forceinline__ unsigned pk2(float lo, float hi) { f32x2 v = {lo, hi}; bf16x2_t b = __builtin_convertvector(v, bf16x2_t); return __builtin_bit_cast(unsigned, b); }
; __device__ __forceinline__ float sigmoidf_(float x) { return rcpf_(1.f + ex2(-x * LOG2E)); }
;     __device__ __forceinline__ void operator()(const f32x4 (&acc)[2][2][4][2], const Unit& u, int wr, int wc, int fr, int fq) const {
;     ...
; #pragma unroll
;         for (int ai = 0; ai < 2; ++ai)
; #pragma unroll
;             for (int m = 0; m < 4; ++m) {
;                 bf16_t* rowp = gate ? G + ((size_t)((((u.pn - gate0 / BM) >> 3) * 64 + u.pm) * 8 + ((u.pn - gate0 / BM) & 7)) * 256 + (wr * 64 + fr + ai * HALF + m * 16)) * 256 + wc * 32 + 8 * fq
;                                     : O + (size_t)(row0 + ai * HALF + m * 16) * ldc + col0;
; #pragma unroll
;                 for (int bj = 0; bj < 2; ++bj) { f32x4 v0 = acc[ai][bj][m][0], v1 = acc[ai][bj][m][1];
;                     if (gate) {
; #pragma unroll
;                         for (int j = 0; j < 4; ++j) { v0[j] = sigmoidf_(v0[j] + gb[bj][0][j]); v1[j] = sigmoidf_(v1[j] + gb[bj][1][j]); } }
;                     u32x4 w; w.x = pk2(v0[0], v0[1]); w.y = pk2(v0[2], v0[3]); w.z = pk2(v1[0], v1[1]); w.w = pk2(v1[2], v1[3]);
;                     *(u32x4*)(rowp + bj * HALF) = w; } }
.LBB0_160:
	v_cvt_pk_bf16_f32 v126, v126, v127
	v_cvt_pk_bf16_f32 v127, v128, v129
	v_cvt_pk_bf16_f32 v128, v122, v123
	v_cvt_pk_bf16_f32 v129, v124, v125
	s_and_b64 vcc, exec, s[6:7]
	s_mov_b64 s[24:25], -1
	global_store_dwordx4 v[130:131], v[126:129], off nt
	s_cbranch_vccnz .LBB0_162
	s_mov_b64 s[24:25], 0

; __device__ __forceinline__ unsigned pk2(float lo, float hi) { f32x2 v = {lo, hi}; bf16x2_t b = __builtin_convertvector(v, bf16x2_t); return __builtin_bit_cast(unsigned, b); }
; __device__ __forceinline__ float sigmoidf_(float x) { return rcpf_(1.f + ex2(-x * LOG2E)); }
;     __device__ __forceinline__ void operator()(const f32x4 (&acc)[2][2][4][2], const Unit& u, int wr, int wc, int fr, int fq) const {
;     ...
; #pragma unroll
;         for (int ai = 0; ai < 2; ++ai)
; #pragma unroll
;             for (int m = 0; m < 4; ++m) {
;                 bf16_t* rowp = gate ? G + ((size_t)((((u.pn - gate0 / BM) >> 3) * 64 + u.pm) * 8 + ((u.pn - gate0 / BM) & 7)) * 256 + (wr * 64 + fr + ai * HALF + m * 16)) * 256 + wc * 32 + 8 * fq
;                                     : O + (size_t)(row0 + ai * HALF + m * 16) * ldc + col0;
; #pragma unroll
;                 for (int bj = 0; bj < 2; ++bj) { f32x4 v0 = acc[ai][bj][m][0], v1 = acc[ai][bj][m][1];
;                     if (gate) {
; #pragma unroll
;                         for (int j = 0; j < 4; ++j) { v0[j] = sigmoidf_(v0[j] + gb[bj][0][j]); v1[j] = sigmoidf_(v1[j] + gb[bj][1][j]); } }
;                     u32x4 w; w.x = pk2(v0[0], v0[1]); w.y = pk2(v0[2], v0[3]); w.z = pk2(v1[0], v1[1]); w.w = pk2(v1[2], v1[3]);
;                     *(u32x4*)(rowp + bj * HALF) = w; } }
.LBB0_164:
	v_cvt_pk_bf16_f32 v118, v118, v119
	v_cvt_pk_bf16_f32 v119, v120, v121
	v_cvt_pk_bf16_f32 v120, v114, v115
	v_cvt_pk_bf16_f32 v121, v116, v117
	s_and_b64 vcc, exec, s[6:7]
	s_mov_b64 s[24:25], -1
	global_store_dwordx4 v[130:131], v[118:121], off offset:256 nt
	s_cbranch_vccnz .LBB0_168
	v_or_b32_e32 v114, 32, v176
	v_ashrrev_i32_e32 v115, 31, v114
	v_lshlrev_b64 v[114:115], 14, v[114:115]
	v_lshl_add_u64 v[114:115], s[2:3], 0, v[114:115]
	v_lshl_add_u64 v[114:115], v[174:175], 1, v[114:115]
	s_cbranch_execz .LBB0_169

; __device__ __forceinline__ unsigned pk2(float lo, float hi) { f32x2 v = {lo, hi}; bf16x2_t b = __builtin_convertvector(v, bf16x2_t); return __builtin_bit_cast(unsigned, b); }
; __device__ __forceinline__ float sigmoidf_(float x) { return rcpf_(1.f + ex2(-x * LOG2E)); }
;     __device__ __forceinline__ void operator()(const f32x4 (&acc)[2][2][4][2], const Unit& u, int wr, int wc, int fr, int fq) const {
;     ...
; #pragma unroll
;         for (int ai = 0; ai < 2; ++ai)
; #pragma unroll
;             for (int m = 0; m < 4; ++m) {
;                 bf16_t* rowp = gate ? G + ((size_t)((((u.pn - gate0 / BM) >> 3) * 64 + u.pm) * 8 + ((u.pn - gate0 / BM) & 7)) * 256 + (wr * 64 + fr + ai * HALF + m * 16)) * 256 + wc * 32 + 8 * fq
;                                     : O + (size_t)(row0 + ai * HALF + m * 16) * ldc + col0;
; #pragma unroll
;                 for (int bj = 0; bj < 2; ++bj) { f32x4 v0 = acc[ai][bj][m][0], v1 = acc[ai][bj][m][1];
;                     if (gate) {
; #pragma unroll
;                         for (int j = 0; j < 4; ++j) { v0[j] = sigmoidf_(v0[j] + gb[bj][0][j]); v1[j] = sigmoidf_(v1[j] + gb[bj][1][j]); } }
;                     u32x4 w; w.x = pk2(v0[0], v0[1]); w.y = pk2(v0[2], v0[3]); w.z = pk2(v1[0], v1[1]); w.w = pk2(v1[2], v1[3]);
;                     *(u32x4*)(rowp + bj * HALF) = w; } }
.LBB0_172:
	v_cvt_pk_bf16_f32 v110, v110, v111
	v_cvt_pk_bf16_f32 v111, v112, v113
	v_cvt_pk_bf16_f32 v112, v106, v107
	v_cvt_pk_bf16_f32 v113, v108, v109
	s_and_b64 vcc, exec, s[6:7]
	s_mov_b64 s[24:25], -1
	global_store_dwordx4 v[114:115], v[110:113], off nt
	s_cbranch_vccnz .LBB0_174
	s_mov_b64 s[24:25], 0

; __device__ __forceinline__ unsigned pk2(float lo, float hi) { f32x2 v = {lo, hi}; bf16x2_t b = __builtin_convertvector(v, bf16x2_t); return __builtin_bit_cast(unsigned, b); }
; __device__ __forceinline__ float sigmoidf_(float x) { return rcpf_(1.f + ex2(-x * LOG2E)); }
;     __device__ __forceinline__ void operator()(const f32x4 (&acc)[2][2][4][2], const Unit& u, int wr, int wc, int fr, int fq) const {
;     ...
; #pragma unroll
;         for (int ai = 0; ai < 2; ++ai)
; #pragma unroll
;             for (int m = 0; m < 4; ++m) {
;                 bf16_t* rowp = gate ? G + ((size_t)((((u.pn - gate0 / BM) >> 3) * 64 + u.pm) * 8 + ((u.pn - gate0 / BM) & 7)) * 256 + (wr * 64 + fr + ai * HALF + m * 16)) * 256 + wc * 32 + 8 * fq
;                                     : O + (size_t)(row0 + ai * HALF + m * 16) * ldc + col0;
; #pragma unroll
;                 for (int bj = 0; bj < 2; ++bj) { f32x4 v0 = acc[ai][bj][m][0], v1 = acc[ai][bj][m][1];
;                     if (gate) {
; #pragma unroll
;                         for (int j = 0; j < 4; ++j) { v0[j] = sigmoidf_(v0[j] + gb[bj][0][j]); v1[j] = sigmoidf_(v1[j] + gb[bj][1][j]); } }
;                     u32x4 w; w.x = pk2(v0[0], v0[1]); w.y = pk2(v0[2], v0[3]); w.z = pk2(v1[0], v1[1]); w.w = pk2(v1[2], v1[3]);
;                     *(u32x4*)(rowp + bj * HALF) = w; } }
.LBB0_176:
	v_cvt_pk_bf16_f32 v102, v102, v103
	v_cvt_pk_bf16_f32 v103, v104, v105
	v_cvt_pk_bf16_f32 v104, v98, v99
	v_cvt_pk_bf16_f32 v105, v100, v101
	s_and_b64 vcc, exec, s[6:7]
	s_mov_b64 s[24:25], -1
	global_store_dwordx4 v[114:115], v[102:105], off offset:256 nt
	s_cbranch_vccnz .LBB0_180
	v_or_b32_e32 v98, 48, v176
	v_ashrrev_i32_e32 v99, 31, v98
	v_lshlrev_b64 v[98:99], 14, v[98:99]
	v_lshl_add_u64 v[98:99], s[2:3], 0, v[98:99]
	v_lshl_add_u64 v[98:99], v[174:175], 1, v[98:99]
	s_cbranch_execz .LBB0_181

; __device__ __forceinline__ unsigned pk2(float lo, float hi) { f32x2 v = {lo, hi}; bf16x2_t b = __builtin_convertvector(v, bf16x2_t); return __builtin_bit_cast(unsigned, b); }
; __device__ __forceinline__ float sigmoidf_(float x) { return rcpf_(1.f + ex2(-x * LOG2E)); }
;     __device__ __forceinline__ void operator()(const f32x4 (&acc)[2][2][4][2], const Unit& u, int wr, int wc, int fr, int fq) const {
;     ...
; #pragma unroll
;         for (int ai = 0; ai < 2; ++ai)
; #pragma unroll
;             for (int m = 0; m < 4; ++m) {
;                 bf16_t* rowp = gate ? G + ((size_t)((((u.pn - gate0 / BM) >> 3) * 64 + u.pm) * 8 + ((u.pn - gate0 / BM) & 7)) * 256 + (wr * 64 + fr + ai * HALF + m * 16)) * 256 + wc * 32 + 8 * fq
;                                     : O + (size_t)(row0 + ai * HALF + m * 16) * ldc + col0;
; #pragma unroll
;                 for (int bj = 0; bj < 2; ++bj) { f32x4 v0 = acc[ai][bj][m][0], v1 = acc[ai][bj][m][1];
;                     if (gate) {
; #pragma unroll
;                         for (int j = 0; j < 4; ++j) { v0[j] = sigmoidf_(v0[j] + gb[bj][0][j]); v1[j] = sigmoidf_(v1[j] + gb[bj][1][j]); } }
;                     u32x4 w; w.x = pk2(v0[0], v0[1]); w.y = pk2(v0[2], v0[3]); w.z = pk2(v1[0], v1[1]); w.w = pk2(v1[2], v1[3]);
;                     *(u32x4*)(rowp + bj * HALF) = w; } }
.LBB0_184:
	v_cvt_pk_bf16_f32 v94, v94, v95
	v_cvt_pk_bf16_f32 v95, v96, v97
	v_cvt_pk_bf16_f32 v96, v90, v91
	v_cvt_pk_bf16_f32 v97, v92, v93
	s_and_b64 vcc, exec, s[6:7]
	s_mov_b64 s[24:25], -1
	global_store_dwordx4 v[98:99], v[94:97], off nt
	s_cbranch_vccnz .LBB0_186
	s_mov_b64 s[24:25], 0

; __device__ __forceinline__ unsigned pk2(float lo, float hi) { f32x2 v = {lo, hi}; bf16x2_t b = __builtin_convertvector(v, bf16x2_t); return __builtin_bit_cast(unsigned, b); }
; __device__ __forceinline__ float sigmoidf_(float x) { return rcpf_(1.f + ex2(-x * LOG2E)); }
;     __device__ __forceinline__ void operator()(const f32x4 (&acc)[2][2][4][2], const Unit& u, int wr, int wc, int fr, int fq) const {
;     ...
; #pragma unroll
;         for (int ai = 0; ai < 2; ++ai)
; #pragma unroll
;             for (int m = 0; m < 4; ++m) {
;                 bf16_t* rowp = gate ? G + ((size_t)((((u.pn - gate0 / BM) >> 3) * 64 + u.pm) * 8 + ((u.pn - gate0 / BM) & 7)) * 256 + (wr * 64 + fr + ai * HALF + m * 16)) * 256 + wc * 32 + 8 * fq
;                                     : O + (size_t)(row0 + ai * HALF + m * 16) * ldc + col0;
; #pragma unroll
;                 for (int bj = 0; bj < 2; ++bj) { f32x4 v0 = acc[ai][bj][m][0], v1 = acc[ai][bj][m][1];
;                     if (gate) {
; #pragma unroll
;                         for (int j = 0; j < 4; ++j) { v0[j] = sigmoidf_(v0[j] + gb[bj][0][j]); v1[j] = sigmoidf_(v1[j] + gb[bj][1][j]); } }
;                     u32x4 w; w.x = pk2(v0[0], v0[1]); w.y = pk2(v0[2], v0[3]); w.z = pk2(v1[0], v1[1]); w.w = pk2(v1[2], v1[3]);
;                     *(u32x4*)(rowp + bj * HALF) = w; } }
.LBB0_188:
	v_cvt_pk_bf16_f32 v86, v86, v87
	v_cvt_pk_bf16_f32 v87, v88, v89
	v_cvt_pk_bf16_f32 v88, v82, v83
	v_cvt_pk_bf16_f32 v89, v84, v85
	s_and_b64 vcc, exec, s[6:7]
	s_mov_b64 s[24:25], -1
	global_store_dwordx4 v[98:99], v[86:89], off offset:256 nt
	s_cbranch_vccnz .LBB0_192
	v_lshlrev_b64 v[82:83], 14, v[176:177]
	v_lshl_add_u64 v[82:83], s[2:3], 0, v[82:83]
	v_lshl_add_u64 v[82:83], v[174:175], 1, v[82:83]
	s_mov_b64 s[24:25], 0x200000
	v_lshl_add_u64 v[82:83], v[82:83], 0, s[24:25]
	s_cbranch_execz .LBB0_193

; __device__ __forceinline__ unsigned pk2(float lo, float hi) { f32x2 v = {lo, hi}; bf16x2_t b = __builtin_convertvector(v, bf16x2_t); return __builtin_bit_cast(unsigned, b); }
; __device__ __forceinline__ float sigmoidf_(float x) { return rcpf_(1.f + ex2(-x * LOG2E)); }
;     __device__ __forceinline__ void operator()(const f32x4 (&acc)[2][2][4][2], const Unit& u, int wr, int wc, int fr, int fq) const {
;     ...
; #pragma unroll
;         for (int ai = 0; ai < 2; ++ai)
; #pragma unroll
;             for (int m = 0; m < 4; ++m) {
;                 bf16_t* rowp = gate ? G + ((size_t)((((u.pn - gate0 / BM) >> 3) * 64 + u.pm) * 8 + ((u.pn - gate0 / BM) & 7)) * 256 + (wr * 64 + fr + ai * HALF + m * 16)) * 256 + wc * 32 + 8 * fq
;                                     : O + (size_t)(row0 + ai * HALF + m * 16) * ldc + col0;
; #pragma unroll
;                 for (int bj = 0; bj < 2; ++bj) { f32x4 v0 = acc[ai][bj][m][0], v1 = acc[ai][bj][m][1];
;                     if (gate) {
; #pragma unroll
;                         for (int j = 0; j < 4; ++j) { v0[j] = sigmoidf_(v0[j] + gb[bj][0][j]); v1[j] = sigmoidf_(v1[j] + gb[bj][1][j]); } }
;                     u32x4 w; w.x = pk2(v0[0], v0[1]); w.y = pk2(v0[2], v0[3]); w.z = pk2(v1[0], v1[1]); w.w = pk2(v1[2], v1[3]);
;                     *(u32x4*)(rowp + bj * HALF) = w; } }
.LBB0_196:
	v_cvt_pk_bf16_f32 v70, v70, v71
	v_cvt_pk_bf16_f32 v71, v72, v73
	v_cvt_pk_bf16_f32 v72, v66, v67
	v_cvt_pk_bf16_f32 v73, v68, v69
	s_and_b64 vcc, exec, s[6:7]
	s_mov_b64 s[24:25], -1
	global_store_dwordx4 v[82:83], v[70:73], off nt
	s_cbranch_vccnz .LBB0_198
	s_mov_b64 s[24:25], 0

; __device__ __forceinline__ unsigned pk2(float lo, float hi) { f32x2 v = {lo, hi}; bf16x2_t b = __builtin_convertvector(v, bf16x2_t); return __builtin_bit_cast(unsigned, b); }
; __device__ __forceinline__ float sigmoidf_(float x) { return rcpf_(1.f + ex2(-x * LOG2E)); }
;     __device__ __forceinline__ void operator()(const f32x4 (&acc)[2][2][4][2], const Unit& u, int wr, int wc, int fr, int fq) const {
;     ...
; #pragma unroll
;         for (int ai = 0; ai < 2; ++ai)
; #pragma unroll
;             for (int m = 0; m < 4; ++m) {
;                 bf16_t* rowp = gate ? G + ((size_t)((((u.pn - gate0 / BM) >> 3) * 64 + u.pm) * 8 + ((u.pn - gate0 / BM) & 7)) * 256 + (wr * 64 + fr + ai * HALF + m * 16)) * 256 + wc * 32 + 8 * fq
;                                     : O + (size_t)(row0 + ai * HALF + m * 16) * ldc + col0;
; #pragma unroll
;                 for (int bj = 0; bj < 2; ++bj) { f32x4 v0 = acc[ai][bj][m][0], v1 = acc[ai][bj][m][1];
;                     if (gate) {
; #pragma unroll
;                         for (int j = 0; j < 4; ++j) { v0[j] = sigmoidf_(v0[j] + gb[bj][0][j]); v1[j] = sigmoidf_(v1[j] + gb[bj][1][j]); } }
;                     u32x4 w; w.x = pk2(v0[0], v0[1]); w.y = pk2(v0[2], v0[3]); w.z = pk2(v1[0], v1[1]); w.w = pk2(v1[2], v1[3]);
;                     *(u32x4*)(rowp + bj * HALF) = w; } }
.LBB0_200:
	v_cvt_pk_bf16_f32 v54, v54, v55
	v_cvt_pk_bf16_f32 v55, v56, v57
	v_cvt_pk_bf16_f32 v56, v50, v51
	v_cvt_pk_bf16_f32 v57, v52, v53
	s_and_b64 vcc, exec, s[6:7]
	s_mov_b64 s[24:25], -1
	global_store_dwordx4 v[82:83], v[54:57], off offset:256 nt
	s_cbranch_vccnz .LBB0_204
	v_lshlrev_b64 v[50:51], 14, v[176:177]
	v_lshl_add_u64 v[50:51], s[2:3], 0, v[50:51]
	v_lshl_add_u64 v[50:51], v[174:175], 1, v[50:51]
	s_mov_b64 s[24:25], 0x240000
	v_lshl_add_u64 v[50:51], v[50:51], 0, s[24:25]
	s_cbranch_execz .LBB0_205

; __device__ __forceinline__ unsigned pk2(float lo, float hi) { f32x2 v = {lo, hi}; bf16x2_t b = __builtin_convertvector(v, bf16x2_t); return __builtin_bit_cast(unsigned, b); }
; __device__ __forceinline__ float sigmoidf_(float x) { return rcpf_(1.f + ex2(-x * LOG2E)); }
;     __device__ __forceinline__ void operator()(const f32x4 (&acc)[2][2][4][2], const Unit& u, int wr, int wc, int fr, int fq) const {
;     ...
; #pragma unroll
;         for (int ai = 0; ai < 2; ++ai)
; #pragma unroll
;             for (int m = 0; m < 4; ++m) {
;                 bf16_t* rowp = gate ? G + ((size_t)((((u.pn - gate0 / BM) >> 3) * 64 + u.pm) * 8 + ((u.pn - gate0 / BM) & 7)) * 256 + (wr * 64 + fr + ai * HALF + m * 16)) * 256 + wc * 32 + 8 * fq
;                                     : O + (size_t)(row0 + ai * HALF + m * 16) * ldc + col0;
; #pragma unroll
;                 for (int bj = 0; bj < 2; ++bj) { f32x4 v0 = acc[ai][bj][m][0], v1 = acc[ai][bj][m][1];
;                     if (gate) {
; #pragma unroll
;                         for (int j = 0; j < 4; ++j) { v0[j] = sigmoidf_(v0[j] + gb[bj][0][j]); v1[j] = sigmoidf_(v1[j] + gb[bj][1][j]); } }
;                     u32x4 w; w.x = pk2(v0[0], v0[1]); w.y = pk2(v0[2], v0[3]); w.z = pk2(v1[0], v1[1]); w.w = pk2(v1[2], v1[3]);
;                     *(u32x4*)(rowp + bj * HALF) = w; } }
.LBB0_208:
	v_cvt_pk_bf16_f32 v46, v46, v47
	v_cvt_pk_bf16_f32 v47, v48, v49
	v_cvt_pk_bf16_f32 v48, v42, v43
	v_cvt_pk_bf16_f32 v49, v44, v45
	s_and_b64 vcc, exec, s[6:7]
	s_mov_b64 s[24:25], -1
	global_store_dwordx4 v[50:51], v[46:49], off nt
	s_cbranch_vccnz .LBB0_210
	s_mov_b64 s[24:25], 0

; __device__ __forceinline__ unsigned pk2(float lo, float hi) { f32x2 v = {lo, hi}; bf16x2_t b = __builtin_convertvector(v, bf16x2_t); return __builtin_bit_cast(unsigned, b); }
; __device__ __forceinline__ float sigmoidf_(float x) { return rcpf_(1.f + ex2(-x * LOG2E)); }
;     __device__ __forceinline__ void operator()(const f32x4 (&acc)[2][2][4][2], const Unit& u, int wr, int wc, int fr, int fq) const {
;     ...
; #pragma unroll
;         for (int ai = 0; ai < 2; ++ai)
; #pragma unroll
;             for (int m = 0; m < 4; ++m) {
;                 bf16_t* rowp = gate ? G + ((size_t)((((u.pn - gate0 / BM) >> 3) * 64 + u.pm) * 8 + ((u.pn - gate0 / BM) & 7)) * 256 + (wr * 64 + fr + ai * HALF + m * 16)) * 256 + wc * 32 + 8 * fq
;                                     : O + (size_t)(row0 + ai * HALF + m * 16) * ldc + col0;
; #pragma unroll
;                 for (int bj = 0; bj < 2; ++bj) { f32x4 v0 = acc[ai][bj][m][0], v1 = acc[ai][bj][m][1];
;                     if (gate) {
; #pragma unroll
;                         for (int j = 0; j < 4; ++j) { v0[j] = sigmoidf_(v0[j] + gb[bj][0][j]); v1[j] = sigmoidf_(v1[j] + gb[bj][1][j]); } }
;                     u32x4 w; w.x = pk2(v0[0], v0[1]); w.y = pk2(v0[2], v0[3]); w.z = pk2(v1[0], v1[1]); w.w = pk2(v1[2], v1[3]);
;                     *(u32x4*)(rowp + bj * HALF) = w; } }
.LBB0_212:
	v_cvt_pk_bf16_f32 v38, v38, v39
	v_cvt_pk_bf16_f32 v39, v40, v41
	v_cvt_pk_bf16_f32 v40, v34, v35
	v_cvt_pk_bf16_f32 v41, v36, v37
	s_and_b64 vcc, exec, s[6:7]
	s_mov_b64 s[24:25], -1
	global_store_dwordx4 v[50:51], v[38:41], off offset:256 nt
	s_cbranch_vccnz .LBB0_216
	v_lshlrev_b64 v[34:35], 14, v[176:177]
	v_lshl_add_u64 v[34:35], s[2:3], 0, v[34:35]
	v_lshl_add_u64 v[34:35], v[174:175], 1, v[34:35]
	s_mov_b64 s[24:25], 0x280000
	v_lshl_add_u64 v[34:35], v[34:35], 0, s[24:25]
	s_cbranch_execz .LBB0_217

; __device__ __forceinline__ unsigned pk2(float lo, float hi) { f32x2 v = {lo, hi}; bf16x2_t b = __builtin_convertvector(v, bf16x2_t); return __builtin_bit_cast(unsigned, b); }
; __device__ __forceinline__ float sigmoidf_(float x) { return rcpf_(1.f + ex2(-x * LOG2E)); }
;     __device__ __forceinline__ void operator()(const f32x4 (&acc)[2][2][4][2], const Unit& u, int wr, int wc, int fr, int fq) const {
;     ...
; #pragma unroll
;         for (int ai = 0; ai < 2; ++ai)
; #pragma unroll
;             for (int m = 0; m < 4; ++m) {
;                 bf16_t* rowp = gate ? G + ((size_t)((((u.pn - gate0 / BM) >> 3) * 64 + u.pm) * 8 + ((u.pn - gate0 / BM) & 7)) * 256 + (wr * 64 + fr + ai * HALF + m * 16)) * 256 + wc * 32 + 8 * fq
;                                     : O + (size_t)(row0 + ai * HALF + m * 16) * ldc + col0;
; #pragma unroll
;                 for (int bj = 0; bj < 2; ++bj) { f32x4 v0 = acc[ai][bj][m][0], v1 = acc[ai][bj][m][1];
;                     if (gate) {
; #pragma unroll
;                         for (int j = 0; j < 4; ++j) { v0[j] = sigmoidf_(v0[j] + gb[bj][0][j]); v1[j] = sigmoidf_(v1[j] + gb[bj][1][j]); } }
;                     u32x4 w; w.x = pk2(v0[0], v0[1]); w.y = pk2(v0[2], v0[3]); w.z = pk2(v1[0], v1[1]); w.w = pk2(v1[2], v1[3]);
;                     *(u32x4*)(rowp + bj * HALF) = w; } }
.LBB0_220:
	v_cvt_pk_bf16_f32 v30, v30, v31
	v_cvt_pk_bf16_f32 v31, v32, v33
	v_cvt_pk_bf16_f32 v32, v26, v27
	v_cvt_pk_bf16_f32 v33, v28, v29
	s_and_b64 vcc, exec, s[6:7]
	s_mov_b64 s[24:25], -1
	global_store_dwordx4 v[34:35], v[30:33], off nt
	s_cbranch_vccnz .LBB0_222
	s_mov_b64 s[24:25], 0

; __device__ __forceinline__ unsigned pk2(float lo, float hi) { f32x2 v = {lo, hi}; bf16x2_t b = __builtin_convertvector(v, bf16x2_t); return __builtin_bit_cast(unsigned, b); }
; __device__ __forceinline__ float sigmoidf_(float x) { return rcpf_(1.f + ex2(-x * LOG2E)); }
;     __device__ __forceinline__ void operator()(const f32x4 (&acc)[2][2][4][2], const Unit& u, int wr, int wc, int fr, int fq) const {
;     ...
; #pragma unroll
;         for (int ai = 0; ai < 2; ++ai)
; #pragma unroll
;             for (int m = 0; m < 4; ++m) {
;                 bf16_t* rowp = gate ? G + ((size_t)((((u.pn - gate0 / BM) >> 3) * 64 + u.pm) * 8 + ((u.pn - gate0 / BM) & 7)) * 256 + (wr * 64 + fr + ai * HALF + m * 16)) * 256 + wc * 32 + 8 * fq
;                                     : O + (size_t)(row0 + ai * HALF + m * 16) * ldc + col0;
; #pragma unroll
;                 for (int bj = 0; bj < 2; ++bj) { f32x4 v0 = acc[ai][bj][m][0], v1 = acc[ai][bj][m][1];
;                     if (gate) {
; #pragma unroll
;                         for (int j = 0; j < 4; ++j) { v0[j] = sigmoidf_(v0[j] + gb[bj][0][j]); v1[j] = sigmoidf_(v1[j] + gb[bj][1][j]); } }
;                     u32x4 w; w.x = pk2(v0[0], v0[1]); w.y = pk2(v0[2], v0[3]); w.z = pk2(v1[0], v1[1]); w.w = pk2(v1[2], v1[3]);
;                     *(u32x4*)(rowp + bj * HALF) = w; } }
.LBB0_224:
	v_cvt_pk_bf16_f32 v22, v22, v23
	v_cvt_pk_bf16_f32 v23, v24, v25
	v_cvt_pk_bf16_f32 v24, v18, v19
	v_cvt_pk_bf16_f32 v25, v20, v21
	s_and_b64 vcc, exec, s[6:7]
	s_mov_b64 s[24:25], -1
	global_store_dwordx4 v[34:35], v[22:25], off offset:256 nt
	s_cbranch_vccnz .LBB0_228
	v_lshlrev_b64 v[18:19], 14, v[176:177]
	v_lshl_add_u64 v[18:19], s[2:3], 0, v[18:19]
	v_lshl_add_u64 v[18:19], v[174:175], 1, v[18:19]
	s_mov_b64 s[24:25], 0x2c0000
	v_lshl_add_u64 v[18:19], v[18:19], 0, s[24:25]
	s_cbranch_execz .LBB0_229

; __device__ __forceinline__ unsigned pk2(float lo, float hi) { f32x2 v = {lo, hi}; bf16x2_t b = __builtin_convertvector(v, bf16x2_t); return __builtin_bit_cast(unsigned, b); }
; __device__ __forceinline__ float sigmoidf_(float x) { return rcpf_(1.f + ex2(-x * LOG2E)); }
;     __device__ __forceinline__ void operator()(const f32x4 (&acc)[2][2][4][2], const Unit& u, int wr, int wc, int fr, int fq) const {
;     ...
; #pragma unroll
;         for (int ai = 0; ai < 2; ++ai)
; #pragma unroll
;             for (int m = 0; m < 4; ++m) {
;                 bf16_t* rowp = gate ? G + ((size_t)((((u.pn - gate0 / BM) >> 3) * 64 + u.pm) * 8 + ((u.pn - gate0 / BM) & 7)) * 256 + (wr * 64 + fr + ai * HALF + m * 16)) * 256 + wc * 32 + 8 * fq
;                                     : O + (size_t)(row0 + ai * HALF + m * 16) * ldc + col0;
; #pragma unroll
;                 for (int bj = 0; bj < 2; ++bj) { f32x4 v0 = acc[ai][bj][m][0], v1 = acc[ai][bj][m][1];
;                     if (gate) {
; #pragma unroll
;                         for (int j = 0; j < 4; ++j) { v0[j] = sigmoidf_(v0[j] + gb[bj][0][j]); v1[j] = sigmoidf_(v1[j] + gb[bj][1][j]); } }
;                     u32x4 w; w.x = pk2(v0[0], v0[1]); w.y = pk2(v0[2], v0[3]); w.z = pk2(v1[0], v1[1]); w.w = pk2(v1[2], v1[3]);
;                     *(u32x4*)(rowp + bj * HALF) = w; } }
.LBB0_232:
	v_cvt_pk_bf16_f32 v14, v14, v15
	v_cvt_pk_bf16_f32 v15, v16, v17
	v_cvt_pk_bf16_f32 v16, v10, v11
	v_cvt_pk_bf16_f32 v17, v12, v13
	s_and_b64 vcc, exec, s[6:7]
	s_mov_b64 s[6:7], -1
	global_store_dwordx4 v[18:19], v[14:17], off nt
	s_cbranch_vccnz .LBB0_234
	s_mov_b64 s[6:7], 0

; __device__ __forceinline__ unsigned pk2(float lo, float hi) { f32x2 v = {lo, hi}; bf16x2_t b = __builtin_convertvector(v, bf16x2_t); return __builtin_bit_cast(unsigned, b); }
; __device__ __forceinline__ float sigmoidf_(float x) { return rcpf_(1.f + ex2(-x * LOG2E)); }
;     __device__ __forceinline__ void operator()(const f32x4 (&acc)[2][2][4][2], const Unit& u, int wr, int wc, int fr, int fq) const {
;     ...
; #pragma unroll
;         for (int ai = 0; ai < 2; ++ai)
; #pragma unroll
;             for (int m = 0; m < 4; ++m) {
;                 bf16_t* rowp = gate ? G + ((size_t)((((u.pn - gate0 / BM) >> 3) * 64 + u.pm) * 8 + ((u.pn - gate0 / BM) & 7)) * 256 + (wr * 64 + fr + ai * HALF + m * 16)) * 256 + wc * 32 + 8 * fq
;                                     : O + (size_t)(row0 + ai * HALF + m * 16) * ldc + col0;
; #pragma unroll
;                 for (int bj = 0; bj < 2; ++bj) { f32x4 v0 = acc[ai][bj][m][0], v1 = acc[ai][bj][m][1];
;                     if (gate) {
; #pragma unroll
;                         for (int j = 0; j < 4; ++j) { v0[j] = sigmoidf_(v0[j] + gb[bj][0][j]); v1[j] = sigmoidf_(v1[j] + gb[bj][1][j]); } }
;                     u32x4 w; w.x = pk2(v0[0], v0[1]); w.y = pk2(v0[2], v0[3]); w.z = pk2(v1[0], v1[1]); w.w = pk2(v1[2], v1[3]);
;                     *(u32x4*)(rowp + bj * HALF) = w; } }
.LBB0_236:
	v_cvt_pk_bf16_f32 v6, v6, v7
	v_cvt_pk_bf16_f32 v7, v8, v9
	v_cvt_pk_bf16_f32 v8, v2, v3
	v_cvt_pk_bf16_f32 v9, v4, v5
	s_andn2_b64 vcc, exec, s[4:5]
	s_mov_b64 s[4:5], -1
	global_store_dwordx4 v[18:19], v[6:9], off offset:256 nt
	s_cbranch_vccnz .LBB0_131
	s_andn2_b64 vcc, exec, s[0:1]
	s_cbranch_vccnz .LBB0_130
	s_barrier
	s_branch .LBB0_130
